# attention: K/V tile loads issued right after the staging writes that free their registers (one step earlier), tile 1 loaded from the unit prologue
# speedup vs baseline: 1.0099x; 1.0099x over previous
.LBB0_307:
	s_xor_b64 s[86:87], s[4:5], -1
	s_and_b64 s[4:5], s[4:5], exec
	s_cselect_b32 s4, s48, s70
	s_lshl_b32 s5, s4, 7
	v_mov_b32_e32 v206, v192
	s_or_b32 s5, s5, s71
	s_or_b32 s35, s5, s34
	s_waitcnt vmcnt(0)
	v_ashrrev_i32_e32 v4, 1, v206
	v_add_u32_e32 v2, s35, v4
	v_ashrrev_i32_e32 v3, 31, v2
	v_lshlrev_b64 v[2:3], 14, v[2:3]
	v_lshlrev_b32_e32 v0, 7, v206
	v_lshl_add_u64 v[2:3], s[26:27], 0, v[2:3]
	v_and_b32_e32 v0, 0x80, v0
	v_lshl_add_u64 v[30:31], v[2:3], 0, v[0:1]
	v_mul_lo_u32 v2, v4, s29
	v_add_u32_e32 v34, s33, v206
	v_and_b32_e32 v56, 15, v206
	v_and_b32_e32 v58, 3, v206
	v_add3_u32 v54, s75, v2, v0
	v_ashrrev_i32_e32 v55, 4, v34
	v_lshlrev_b32_e32 v0, 3, v56
	v_ashrrev_i32_e32 v57, 2, v34
	v_lshlrev_b32_e32 v34, 3, v58
	v_lshl_or_b32 v0, v55, 13, v0
	v_lshl_or_b32 v42, v57, 11, v34
	v_mov_b32_e32 v43, v1
	v_lshlrev_b64 v[50:51], 1, v[0:1]
	v_lshlrev_b64 v[52:53], 1, v[42:43]
	v_lshl_add_u64 v[38:39], s[44:45], 0, v[50:51]
	v_lshl_add_u64 v[42:43], s[0:1], 0, v[52:53]
	v_lshl_add_u64 v[46:47], s[50:51], 0, v[52:53]
	global_load_dwordx4 v[2:5], v[30:31], off offset:48
	global_load_dwordx4 v[6:9], v[30:31], off offset:32
	global_load_dwordx4 v[10:13], v[30:31], off offset:16
	global_load_dwordx4 v[14:17], v[30:31], off
	global_load_dwordx4 v[18:21], v[30:31], off offset:112
	global_load_dwordx4 v[22:25], v[30:31], off offset:96
	global_load_dwordx4 v[26:29], v[30:31], off offset:80
	s_nop 0
	global_load_dwordx4 v[30:33], v[30:31], off offset:64
	s_nop 0
	global_load_dwordx4 v[34:37], v[38:39], off
	s_nop 0
	global_load_dwordx4 v[38:41], v[38:39], off offset:256
	s_nop 0
	global_load_dwordx4 v[42:45], v[42:43], off
	s_nop 0
	global_load_dwordx4 v[46:49], v[46:47], off
	s_lshl_b32 s28, s4, 2
	s_movk_i32 s4, 0x50
	v_mul_lo_u32 v57, v57, s4
	v_mov_b32_e32 v0, s75
	v_and_b32_e32 v205, 31, v206
	v_ashrrev_i32_e32 v195, 5, v206
	v_mul_lo_u32 v55, v55, s29
	v_and_b32_e32 v214, 2, v58
	v_lshl_add_u32 v214, v214, 4, v57
	v_and_b32_e32 v58, 1, v58
	v_lshl_add_u32 v214, v58, 3, v214
	v_mad_u32_u24 v210, v205, s29, v0
	v_lshlrev_b32_e32 v0, 2, v195
	v_lshl_add_u32 v213, v56, 4, v55
	v_add_u32_e32 v56, 0, v214
	v_add_u32_e32 v55, 0, v213
	v_add_u32_e32 v57, 0x4400, v56
	v_add_u32_e32 v56, 0x6c00, v56
	v_cmp_gt_i32_e64 s[90:91], v0, v205
	v_cmp_lt_i32_e64 s[88:89], v0, v205
	v_or_b32_e32 v59, 2, v0
	v_or_b32_e32 v60, 3, v0
	v_add_u32_e32 v61, 8, v0
	v_add_u32_e32 v62, 9, v0
	v_add_u32_e32 v63, 10, v0
	v_add_u32_e32 v64, 11, v0
	v_add_u32_e32 v65, 16, v0
	s_lshr_b32 s49, s5, 5
	v_cmp_gt_i32_e64 s[92:93], v59, v205
	v_cmp_gt_i32_e64 s[94:95], v60, v205
	v_cmp_gt_i32_e64 s[96:97], v61, v205
	v_cmp_gt_i32_e64 s[4:5], v62, v205
	v_cmp_gt_i32_e64 s[6:7], v63, v205
	v_cmp_gt_i32_e64 s[8:9], v64, v205
	v_cmp_gt_i32_e64 s[10:11], v65, v205
	v_lshl_add_u64 v[188:189], s[60:61], 0, v[52:53]
	v_lshl_add_u64 v[190:191], s[54:55], 0, v[50:51]
	v_mul_u32_u24_e32 v211, 0x110, v205
	v_lshlrev_b32_e32 v209, 4, v195
	v_mul_u32_u24_e32 v212, 0x50, v205
	v_lshlrev_b32_e32 v208, 4, v195
	s_or_b32 s79, s28, 3
	s_mov_b32 s77, 0
	v_mov_b32_e32 v207, 0
	v_mov_b32_e32 v215, 0xff800000
	s_waitcnt vmcnt(0)
	ds_write_b128 v54, v[14:17]
	ds_write_b128 v54, v[10:13] offset:16
	ds_write_b128 v54, v[6:9] offset:32
	ds_write_b128 v54, v[2:5] offset:48
	ds_write_b128 v54, v[30:33] offset:64
	ds_write_b128 v54, v[26:29] offset:80
	ds_write_b128 v54, v[22:25] offset:96
	ds_write_b128 v54, v[18:21] offset:112
	ds_write_b128 v55, v[34:37]
	ds_write_b128 v55, v[38:41] offset:8704
	ds_write2_b64 v57, v[42:43], v[44:45] offset1:2
	ds_write2_b64 v56, v[46:47], v[48:49] offset1:2
	v_add_u32_e32 v2, 17, v0
	v_cmp_gt_i32_e64 s[12:13], v2, v205
	v_add_u32_e32 v2, 18, v0
	v_cmp_gt_i32_e64 s[14:15], v2, v205
	v_add_u32_e32 v2, 19, v0
	v_cmp_gt_i32_e64 s[16:17], v2, v205
	v_add_u32_e32 v2, 24, v0
	v_cmp_gt_i32_e64 s[18:19], v2, v205
	v_add_u32_e32 v2, 25, v0
	v_cmp_gt_i32_e64 s[20:21], v2, v205
	v_add_u32_e32 v2, 26, v0
	v_add_u32_e32 v0, 27, v0
	v_mov_b32_e32 v14, v1
	v_mov_b32_e32 v15, v1
	v_cmp_gt_i32_e64 s[22:23], v2, v205
	v_cmp_gt_i32_e64 s[24:25], v0, v205
	v_mov_b32_e32 v0, v1
	v_mov_b32_e32 v2, v1
	v_mov_b32_e32 v3, v1
	v_mov_b32_e32 v4, v1
	v_mov_b32_e32 v5, v1
	v_mov_b32_e32 v6, v1
	v_mov_b32_e32 v7, v1
	v_mov_b32_e32 v8, v1
	v_mov_b32_e32 v9, v1
	v_mov_b32_e32 v10, v1
	v_mov_b32_e32 v11, v1
	v_mov_b32_e32 v12, v1
	v_mov_b32_e32 v13, v1
	v_mov_b64_e32 v[30:31], v[14:15]
	v_mov_b64_e32 v[46:47], v[14:15]
	v_mov_b64_e32 v[62:63], v[14:15]
	v_mov_b64_e32 v[78:79], v[14:15]
	v_mov_b64_e32 v[94:95], v[14:15]
	v_mov_b64_e32 v[110:111], v[14:15]
	v_mov_b64_e32 v[126:127], v[14:15]
	v_mov_b64_e32 v[142:143], v[14:15]
	v_mov_b64_e32 v[28:29], v[12:13]
	v_mov_b64_e32 v[26:27], v[10:11]
	v_mov_b64_e32 v[24:25], v[8:9]
	v_mov_b64_e32 v[22:23], v[6:7]
	v_mov_b64_e32 v[20:21], v[4:5]
	v_mov_b64_e32 v[18:19], v[2:3]
	v_mov_b64_e32 v[16:17], v[0:1]
	v_mov_b64_e32 v[44:45], v[12:13]
	v_mov_b64_e32 v[42:43], v[10:11]
	v_mov_b64_e32 v[40:41], v[8:9]
	v_mov_b64_e32 v[38:39], v[6:7]
	v_mov_b64_e32 v[36:37], v[4:5]
	v_mov_b64_e32 v[34:35], v[2:3]
	v_mov_b64_e32 v[32:33], v[0:1]
	v_mov_b64_e32 v[60:61], v[12:13]
	v_mov_b64_e32 v[58:59], v[10:11]
	v_mov_b64_e32 v[56:57], v[8:9]
	v_mov_b64_e32 v[54:55], v[6:7]
	v_mov_b64_e32 v[52:53], v[4:5]
	v_mov_b64_e32 v[50:51], v[2:3]
	v_mov_b64_e32 v[48:49], v[0:1]
	v_mov_b64_e32 v[76:77], v[12:13]
	v_mov_b64_e32 v[74:75], v[10:11]
	v_mov_b64_e32 v[72:73], v[8:9]
	v_mov_b64_e32 v[70:71], v[6:7]
	v_mov_b64_e32 v[68:69], v[4:5]
	v_mov_b64_e32 v[66:67], v[2:3]
	v_mov_b64_e32 v[64:65], v[0:1]
	v_mov_b64_e32 v[92:93], v[12:13]
	v_mov_b64_e32 v[90:91], v[10:11]
	v_mov_b64_e32 v[88:89], v[8:9]
	v_mov_b64_e32 v[86:87], v[6:7]
	v_mov_b64_e32 v[84:85], v[4:5]
	v_mov_b64_e32 v[82:83], v[2:3]
	v_mov_b64_e32 v[80:81], v[0:1]
	v_mov_b64_e32 v[108:109], v[12:13]
	v_mov_b64_e32 v[106:107], v[10:11]
	v_mov_b64_e32 v[104:105], v[8:9]
	v_mov_b64_e32 v[102:103], v[6:7]
	v_mov_b64_e32 v[100:101], v[4:5]
	v_mov_b64_e32 v[98:99], v[2:3]
	v_mov_b64_e32 v[96:97], v[0:1]
	v_mov_b64_e32 v[124:125], v[12:13]
	v_mov_b64_e32 v[122:123], v[10:11]
	v_mov_b64_e32 v[120:121], v[8:9]
	v_mov_b64_e32 v[118:119], v[6:7]
	v_mov_b64_e32 v[116:117], v[4:5]
	v_mov_b64_e32 v[114:115], v[2:3]
	v_mov_b64_e32 v[112:113], v[0:1]
	v_mov_b64_e32 v[140:141], v[12:13]
	v_mov_b64_e32 v[138:139], v[10:11]
	v_mov_b64_e32 v[136:137], v[8:9]
	v_mov_b64_e32 v[134:135], v[6:7]
	v_mov_b64_e32 v[132:133], v[4:5]
	v_mov_b64_e32 v[130:131], v[2:3]
	v_mov_b64_e32 v[128:129], v[0:1]
	v_lshl_add_u64 v[2:3], s[30:31], 0, v[190:191]
	v_lshl_add_u64 v[10:11], s[30:31], 0, v[188:189]
	v_add_co_u32_e32 v6, vcc, 0x13481000, v2
	s_nop 1
	v_addc_co_u32_e32 v7, vcc, 0, v3, vcc
	v_add_co_u32_e32 v12, vcc, 0x1f400000, v10
	global_load_dwordx4 v[2:5], v[6:7], off
	s_nop 0
	global_load_dwordx4 v[6:9], v[6:7], off offset:256
	v_addc_co_u32_e32 v13, vcc, 0, v11, vcc
	v_add_co_u32_e32 v176, vcc, 0x1f480000, v10
	s_nop 1
	v_addc_co_u32_e32 v177, vcc, 0, v11, vcc
	global_load_dwordx4 v[10:13], v[12:13], off offset:64
	s_nop 0
	global_load_dwordx4 v[176:179], v[176:177], off offset:64
	s_waitcnt lgkmcnt(0)
	s_barrier
	s_branch .LBB0_310
.LBB0_308:
	v_sub_f32_e32 v0, v160, v215
	v_exp_f32_e32 v0, v0
	v_sub_f32_e32 v160, v161, v215
	v_exp_f32_e32 v160, v160
	v_sub_f32_e32 v161, v162, v215
	v_exp_f32_e32 v161, v161
	v_sub_f32_e32 v162, v163, v215
	v_exp_f32_e32 v162, v162
	v_sub_f32_e32 v164, v164, v215
	v_add_f32_e32 v163, v207, v0
	v_exp_f32_e32 v164, v164
	v_add_f32_e32 v163, v160, v163
	v_add_f32_e32 v163, v161, v163
	v_sub_f32_e32 v165, v165, v215
	v_add_f32_e32 v163, v162, v163
	v_exp_f32_e32 v165, v165
	v_sub_f32_e32 v166, v166, v215
	v_exp_f32_e32 v166, v166
	v_sub_f32_e32 v167, v167, v215
	v_add_f32_e32 v163, v164, v163
	v_cvt_pk_bf16_f32 v160, v0, v160
	v_cvt_pk_bf16_f32 v161, v161, v162
	v_cvt_pk_bf16_f32 v162, v164, v165
	v_sub_f32_e32 v164, v169, v215
	v_exp_f32_e32 v167, v167
	v_sub_f32_e32 v0, v168, v215
	v_exp_f32_e32 v168, v164
	v_sub_f32_e32 v164, v170, v215
	v_exp_f32_e32 v169, v164
	v_sub_f32_e32 v164, v171, v215
	v_add_f32_e32 v163, v165, v163
	v_exp_f32_e32 v170, v164
	v_sub_f32_e32 v164, v172, v215
	v_add_f32_e32 v163, v166, v163
	v_exp_f32_e32 v171, v164
	v_sub_f32_e32 v164, v173, v215
	v_sub_f32_e32 v14, v14, v215
	v_sub_f32_e32 v15, v15, v215
	v_add_f32_e32 v175, v167, v163
	v_cvt_pk_bf16_f32 v163, v166, v167
	v_exp_f32_e32 v0, v0
	v_exp_f32_e32 v172, v164
	v_exp_f32_e32 v14, v14
	v_exp_f32_e32 v15, v15
	v_cvt_pk_bf16_f32 v164, v0, v168
	v_cvt_pk_bf16_f32 v165, v169, v170
	v_cvt_pk_bf16_f32 v166, v171, v172
	v_cvt_pk_bf16_f32 v167, v14, v15
	s_waitcnt lgkmcnt(3)
	v_mfma_f32_32x32x16_bf16 v[128:143], v[148:151], v[160:163], v[128:143]
	s_waitcnt lgkmcnt(1)
	v_mfma_f32_32x32x16_bf16 v[112:127], v[156:159], v[160:163], v[112:127]
	v_mfma_f32_32x32x16_bf16 v[128:143], v[144:147], v[164:167], v[128:143]
	ds_read_b128 v[144:147], v174 offset:25120
	s_waitcnt lgkmcnt(1)
	v_mfma_f32_32x32x16_bf16 v[112:127], v[152:155], v[164:167], v[112:127]
	ds_read_b128 v[148:151], v174 offset:22528
	ds_read_b128 v[152:155], v174 offset:22560
	ds_read_b128 v[156:159], v174 offset:25088
	s_waitcnt lgkmcnt(2)
	v_mfma_f32_32x32x16_bf16 v[96:111], v[148:151], v[160:163], v[96:111]
	s_waitcnt lgkmcnt(0)
	v_mfma_f32_32x32x16_bf16 v[80:95], v[156:159], v[160:163], v[80:95]
	v_mfma_f32_32x32x16_bf16 v[96:111], v[152:155], v[164:167], v[96:111]
	v_mfma_f32_32x32x16_bf16 v[80:95], v[144:147], v[164:167], v[80:95]
	ds_read_b128 v[144:147], v174 offset:30240
	ds_read_b128 v[148:151], v174 offset:27648
	ds_read_b128 v[152:155], v174 offset:27680
	ds_read_b128 v[156:159], v174 offset:30208
	s_waitcnt lgkmcnt(2)
	v_mfma_f32_32x32x16_bf16 v[64:79], v[148:151], v[160:163], v[64:79]
	s_waitcnt lgkmcnt(0)
	v_mfma_f32_32x32x16_bf16 v[48:63], v[156:159], v[160:163], v[48:63]
	v_subrev_u32_e32 v250, s73, v213
	s_waitcnt vmcnt(2)
	ds_write_b128 v250, v[2:5] offset:37888
	ds_write_b128 v250, v[6:9] offset:46592
	s_sub_i32 vcc_lo, s79, s77
	s_cmp_gt_u32 vcc_lo, 1
	s_cbranch_scc0 .Lat_nok
	v_lshl_add_u64 v[2:3], s[30:31], 0, v[190:191]
	s_nop 0
	v_add_co_u32_e32 v6, vcc, 0x13501000, v2
	s_nop 1
	v_addc_co_u32_e32 v7, vcc, 0, v3, vcc
	global_load_dwordx4 v[2:5], v[6:7], off
	s_nop 0
	global_load_dwordx4 v[6:9], v[6:7], off offset:256
.Lat_nok:
	v_mfma_f32_32x32x16_bf16 v[64:79], v[152:155], v[164:167], v[64:79]
	v_mfma_f32_32x32x16_bf16 v[48:63], v[144:147], v[164:167], v[48:63]
	ds_read_b128 v[144:147], v174 offset:35360
	ds_read_b128 v[148:151], v174 offset:32768
	ds_read_b128 v[152:155], v174 offset:32800
	ds_read_b128 v[156:159], v174 offset:35328
	s_waitcnt lgkmcnt(2)
	v_mfma_f32_32x32x16_bf16 v[32:47], v[148:151], v[160:163], v[32:47]
	s_waitcnt lgkmcnt(0)
	v_mfma_f32_32x32x16_bf16 v[16:31], v[156:159], v[160:163], v[16:31]
	v_subrev_u32_e32 v250, s73, v214
	v_add_u32_e32 v216, 0xd800, v250
	v_add_u32_e32 v250, 0x10000, v250
	s_sub_i32 vcc_lo, s79, s77
	s_cmp_gt_u32 vcc_lo, 1
	s_cbranch_scc0 .Lat_vlast
	s_waitcnt vmcnt(2)
	ds_write2_b64 v216, v[10:11], v[12:13] offset1:2
	ds_write2_b64 v250, v[176:177], v[178:179] offset1:2
	v_lshl_add_u64 v[10:11], s[30:31], 0, v[188:189]
	s_nop 0
	v_add_co_u32_e32 v12, vcc, 0x1f400000, v10
	s_nop 1
	v_addc_co_u32_e32 v13, vcc, 0, v11, vcc
	v_add_co_u32_e32 v176, vcc, 0x1f480000, v10
	s_nop 1
	v_addc_co_u32_e32 v177, vcc, 0, v11, vcc
	global_load_dwordx4 v[10:13], v[12:13], off offset:128
	s_nop 0
	global_load_dwordx4 v[176:179], v[176:177], off offset:128
	s_branch .Lat_vdone
.Lat_vlast:
	s_waitcnt vmcnt(0)
	ds_write2_b64 v216, v[10:11], v[12:13] offset1:2
	ds_write2_b64 v250, v[176:177], v[178:179] offset1:2
.Lat_vdone:
	v_mfma_f32_32x32x16_bf16 v[32:47], v[152:155], v[164:167], v[32:47]
	v_mfma_f32_32x32x16_bf16 v[16:31], v[144:147], v[164:167], v[16:31]
	v_add_f32_e32 v0, v0, v175
	v_add_f32_e32 v0, v168, v0
	v_add_f32_e32 v0, v169, v0
	v_add_f32_e32 v0, v170, v0
	v_add_f32_e32 v0, v171, v0
	v_add_f32_e32 v0, v172, v0
	v_add_f32_e32 v0, v14, v0
	v_add_f32_e32 v207, v15, v0
	s_add_i32 s77, s77, 1
	v_lshl_add_u64 v[188:189], v[188:189], 0, 64
	s_mov_b64 vcc, 0x80000
	s_cmp_eq_u32 s79, s77
	v_lshl_add_u64 v[190:191], v[190:191], 0, vcc
	s_branch .Lat_step_end
.LBB0_309:
	s_sub_i32 s73, 0, s73
	v_add_u32_e32 v0, s73, v213
	s_add_i32 s77, s77, 1
	s_waitcnt vmcnt(3)
	ds_write_b128 v0, v[2:5] offset:37888
	s_waitcnt vmcnt(2)
	ds_write_b128 v0, v[6:9] offset:46592
	v_add_u32_e32 v0, s73, v214
	s_mov_b64 vcc, 0x80000
	v_add_u32_e32 v2, 0xd800, v0
	v_add_u32_e32 v0, 0x10000, v0
	v_lshl_add_u64 v[188:189], v[188:189], 0, 64
	v_lshl_add_u64 v[190:191], v[190:191], 0, vcc
	s_waitcnt vmcnt(1)
	ds_write2_b64 v2, v[10:11], v[12:13] offset1:2
	s_waitcnt vmcnt(0)
	ds_write2_b64 v0, v[176:177], v[178:179] offset1:2
	s_cmp_lt_u32 s77, s79
	s_cbranch_scc0 .Lat_sknl
	v_lshl_add_u64 v[2:3], s[30:31], 0, v[190:191]
	v_lshl_add_u64 v[10:11], s[30:31], 0, v[188:189]
	v_add_co_u32_e32 v6, vcc, 0x13481000, v2
	s_nop 1
	v_addc_co_u32_e32 v7, vcc, 0, v3, vcc
	v_add_co_u32_e32 v12, vcc, 0x1f400000, v10
	global_load_dwordx4 v[2:5], v[6:7], off
	s_nop 0
	global_load_dwordx4 v[6:9], v[6:7], off offset:256
	v_addc_co_u32_e32 v13, vcc, 0, v11, vcc
	v_add_co_u32_e32 v176, vcc, 0x1f480000, v10
	s_nop 1
	v_addc_co_u32_e32 v177, vcc, 0, v11, vcc
	global_load_dwordx4 v[10:13], v[12:13], off offset:64
	s_nop 0
	global_load_dwordx4 v[176:179], v[176:177], off offset:64
.Lat_sknl:
	s_cmp_eq_u32 s79, s77

.Lat_nostag:
	s_bitcmp1_b32 s77, 0
	s_cselect_b32 s73, 0x9400, 0
	s_cmp_gt_u32 s77, s49
	s_cbranch_scc1 .LBB0_309
	s_add_i32 vcc_lo, s73, 0
	s_add_i32 vcc_hi, vcc_lo, s78
	v_add3_u32 v0, vcc_hi, v211, v209
	v_add_u32_e32 v14, v210, v209
	ds_read_b128 v[144:147], v0
	ds_read_b128 v[160:163], v0 offset:32
	ds_read_b128 v[148:151], v14
	ds_read_b128 v[164:167], v14 offset:32
	ds_read_b128 v[216:219], v0 offset:64
	ds_read_b128 v[220:223], v0 offset:96
	ds_read_b128 v[224:227], v14 offset:64
	ds_read_b128 v[228:231], v14 offset:96
	v_add_u32_e32 v250, vcc_lo, v212
	s_waitcnt lgkmcnt(5)
	v_mfma_f32_32x32x16_bf16 v[144:159], v[144:147], v[148:151], 0
	s_waitcnt lgkmcnt(4)
	v_mfma_f32_32x32x16_bf16 v[160:175], v[160:163], v[164:167], 0
	s_waitcnt lgkmcnt(1)
	v_mfma_f32_32x32x16_bf16 v[144:159], v[216:219], v[224:227], v[144:159]
	ds_read_b128 v[216:219], v0 offset:128
	ds_read_b128 v[224:227], v0 offset:160
	ds_read_b128 v[232:235], v14 offset:128
	ds_read_b128 v[236:239], v14 offset:160
	ds_read_b128 v[240:243], v0 offset:192
	ds_read_b128 v[244:247], v0 offset:224
	ds_read_b128 v[180:183], v14 offset:192
	ds_read_b128 v[184:187], v14 offset:224
	s_waitcnt lgkmcnt(8)
	v_mfma_f32_32x32x16_bf16 v[160:175], v[220:223], v[228:231], v[160:175]
	s_waitcnt lgkmcnt(5)
	v_mfma_f32_32x32x16_bf16 v[144:159], v[216:219], v[232:235], v[144:159]
	s_waitcnt lgkmcnt(4)
	v_mfma_f32_32x32x16_bf16 v[160:175], v[224:227], v[236:239], v[160:175]
	s_waitcnt lgkmcnt(1)
	v_mfma_f32_32x32x16_bf16 v[144:159], v[240:243], v[180:183], v[144:159]
	s_waitcnt lgkmcnt(0)
	v_mfma_f32_32x32x16_bf16 v[160:175], v[244:247], v[184:187], v[160:175]
	s_nop 11
	v_pk_add_f32 v[14:15], v[158:159], v[174:175]
	v_add_u32_e32 v174, v250, v208
	v_pk_add_f32 v[166:167], v[150:151], v[166:167]
	v_pk_add_f32 v[164:165], v[148:149], v[164:165]
	v_pk_add_f32 v[162:163], v[146:147], v[162:163]
	v_pk_add_f32 v[160:161], v[144:145], v[160:161]
	ds_read_b128 v[148:151], v174 offset:17408
	ds_read_b128 v[144:147], v174 offset:17440
	v_pk_add_f32 v[172:173], v[156:157], v[172:173]
	v_pk_add_f32 v[170:171], v[154:155], v[170:171]
	v_pk_add_f32 v[168:169], v[152:153], v[168:169]
	ds_read_b128 v[156:159], v174 offset:19968
	ds_read_b128 v[152:155], v174 offset:20000
	s_cmp_lg_u32 s49, s77
	s_cbranch_scc1 .LBB0_313
	v_cndmask_b32_e64 v0, v160, v202, s[90:91]
	v_cndmask_b32_e64 v161, v202, v161, s[88:89]
	v_cndmask_b32_e64 v160, v0, v160, s[88:89]
	v_cndmask_b32_e64 v162, v162, v202, s[92:93]
	v_cndmask_b32_e64 v163, v163, v202, s[94:95]
	v_cndmask_b32_e64 v164, v164, v202, s[96:97]
	v_cndmask_b32_e64 v165, v165, v202, s[4:5]
	v_cndmask_b32_e64 v166, v166, v202, s[6:7]
	v_cndmask_b32_e64 v167, v167, v202, s[8:9]
	v_cndmask_b32_e64 v168, v168, v202, s[10:11]
	v_cndmask_b32_e64 v169, v169, v202, s[12:13]
	v_cndmask_b32_e64 v170, v170, v202, s[14:15]
	v_cndmask_b32_e64 v171, v171, v202, s[16:17]
	v_cndmask_b32_e64 v172, v172, v202, s[18:19]
	v_cndmask_b32_e64 v173, v173, v202, s[20:21]
	v_cndmask_b32_e64 v14, v14, v202, s[22:23]
	v_cndmask_b32_e64 v15, v15, v202, s[24:25]
